# mixer-A tile loop: log2-weight table LDS reads issued together right after the QK MFMAs instead of one per consumer
# speedup vs baseline: 1.0039x; 1.0039x over previous
.LBB0_488:
	s_waitcnt lgkmcnt(0)
	s_mul_i32 s0, s8, 0x9000
	v_lshlrev_b32_e32 v32, 1, v108
	v_add3_u32 v106, s0, v118, v32
	v_mov_b32_e32 v128, v33
	ds_read_b128 v[32:35], v106 offset:4608
	ds_read_b128 v[36:39], v106
	ds_read_b128 v[130:133], v106 offset:32
	ds_read_b128 v[134:137], v106 offset:4640
	s_waitcnt lgkmcnt(2)
	v_mfma_f32_32x32x16_bf16 v[48:63], v[36:39], v[64:67], 0
	v_cmp_gt_i32_e32 vcc, 0, v126
	s_and_b64 vcc, exec, vcc
	v_mfma_f32_32x32x16_bf16 v[32:47], v[32:35], v[64:67], 0
	s_waitcnt lgkmcnt(1)
	v_mfma_f32_32x32x16_bf16 v[48:63], v[130:133], v[68:71], v[48:63]
	s_waitcnt lgkmcnt(0)
	v_mfma_f32_32x32x16_bf16 v[32:47], v[134:137], v[68:71], v[32:47]
	ds_read_b128 v[130:133], v106 offset:64
	ds_read_b128 v[134:137], v106 offset:4672
	s_waitcnt lgkmcnt(1)
	v_mfma_f32_32x32x16_bf16 v[48:63], v[130:133], v[72:75], v[48:63]
	s_waitcnt lgkmcnt(0)
	v_mfma_f32_32x32x16_bf16 v[32:47], v[134:137], v[72:75], v[32:47]
	ds_read_b128 v[130:133], v106 offset:96
	ds_read_b128 v[134:137], v106 offset:4704
	s_waitcnt lgkmcnt(1)
	v_mfma_f32_32x32x16_bf16 v[48:63], v[130:133], v[76:79], v[48:63]
	s_waitcnt lgkmcnt(0)
	v_mfma_f32_32x32x16_bf16 v[32:47], v[134:137], v[76:79], v[32:47]
	ds_read2_b32 v[146:147], v127 offset0:58 offset1:59
	ds_read2_b32 v[148:149], v127 offset0:2 offset1:3
	ds_read2_b32 v[150:151], v127 offset1:1
	ds_read2_b32 v[152:153], v127 offset0:18 offset1:19
	ds_read2_b32 v[154:155], v127 offset0:16 offset1:17
	ds_read2_b32 v[156:157], v127 offset0:56 offset1:57
	ds_read2_b32 v[158:159], v127 offset0:10 offset1:11
	ds_read2_b32 v[160:161], v127 offset0:8 offset1:9
	ds_read2_b32 v[162:163], v127 offset0:50 offset1:51
	ds_read2_b32 v[164:165], v127 offset0:48 offset1:49
	ds_read2_b32 v[166:167], v127 offset0:42 offset1:43
	ds_read2_b32 v[168:169], v127 offset0:40 offset1:41
	ds_read2_b32 v[170:171], v127 offset0:34 offset1:35
	ds_read2_b32 v[172:173], v127 offset0:32 offset1:33
	ds_read2_b32 v[174:175], v127 offset0:26 offset1:27
	ds_read2_b32 v[176:177], v127 offset0:24 offset1:25
	s_waitcnt lgkmcnt(15)
	v_fmamk_f32 v107, v48, 0x3e38aa3b, v147
	v_fmamk_f32 v106, v49, 0x3e38aa3b, v146
	v_max3_f32 v129, v128, v107, v106
	s_waitcnt lgkmcnt(10)
	v_fmamk_f32 v49, v50, 0x3e38aa3b, v157
	v_fmamk_f32 v48, v51, 0x3e38aa3b, v156
	v_max3_f32 v129, v129, v49, v48
	s_waitcnt lgkmcnt(9)
	v_fmamk_f32 v134, v41, 0x3e38aa3b, v158
	s_waitcnt lgkmcnt(8)
	v_fmamk_f32 v136, v43, 0x3e38aa3b, v160
	v_fmamk_f32 v138, v45, 0x3e38aa3b, v148
	s_waitcnt lgkmcnt(7)
	v_fmamk_f32 v51, v52, 0x3e38aa3b, v163
	v_fmamk_f32 v50, v53, 0x3e38aa3b, v162
	v_max3_f32 v129, v129, v51, v50
	v_fmamk_f32 v130, v37, 0x3e38aa3b, v152
	v_fmamk_f32 v132, v39, 0x3e38aa3b, v154
	v_fmamk_f32 v140, v47, 0x3e38aa3b, v150
	s_waitcnt lgkmcnt(6)
	v_fmamk_f32 v53, v54, 0x3e38aa3b, v165
	v_fmamk_f32 v52, v55, 0x3e38aa3b, v164
	v_max3_f32 v129, v129, v53, v52
	s_waitcnt lgkmcnt(5)
	v_fmamk_f32 v55, v56, 0x3e38aa3b, v167
	v_fmamk_f32 v54, v57, 0x3e38aa3b, v166
	v_max3_f32 v129, v129, v55, v54
	s_waitcnt lgkmcnt(4)
	v_fmamk_f32 v57, v58, 0x3e38aa3b, v169
	v_fmamk_f32 v56, v59, 0x3e38aa3b, v168
	v_max3_f32 v129, v129, v57, v56
	s_waitcnt lgkmcnt(3)
	v_fmamk_f32 v59, v60, 0x3e38aa3b, v171
	v_fmamk_f32 v58, v61, 0x3e38aa3b, v170
	v_max3_f32 v129, v129, v59, v58
	s_waitcnt lgkmcnt(2)
	v_fmamk_f32 v61, v62, 0x3e38aa3b, v173
	v_fmamk_f32 v60, v63, 0x3e38aa3b, v172
	v_max3_f32 v129, v129, v61, v60
	s_waitcnt lgkmcnt(1)
	v_fmamk_f32 v63, v32, 0x3e38aa3b, v175
	v_fmamk_f32 v62, v33, 0x3e38aa3b, v174
	v_max3_f32 v129, v129, v63, v62
	s_waitcnt lgkmcnt(0)
	v_fmamk_f32 v142, v34, 0x3e38aa3b, v177
	v_fmamk_f32 v32, v35, 0x3e38aa3b, v176
	v_max3_f32 v33, v129, v142, v32
	v_fmamk_f32 v129, v36, 0x3e38aa3b, v153
	v_max3_f32 v33, v33, v129, v130
	v_fmamk_f32 v131, v38, 0x3e38aa3b, v155
	v_max3_f32 v33, v33, v131, v132
	v_fmamk_f32 v133, v40, 0x3e38aa3b, v159
	v_max3_f32 v33, v33, v133, v134
	v_fmamk_f32 v135, v42, 0x3e38aa3b, v161
	v_max3_f32 v33, v33, v135, v136
	v_fmamk_f32 v137, v44, 0x3e38aa3b, v149
	v_max3_f32 v33, v33, v137, v138
	v_fmamk_f32 v139, v46, 0x3e38aa3b, v151
	v_max3_f32 v33, v33, v139, v140
	ds_bpermute_b32 v34, v119, v33
	s_waitcnt lgkmcnt(0)
	v_max_f32_e32 v34, v34, v34
	v_max_f32_e32 v33, v33, v34
	v_sub_f32_e32 v32, v32, v33
	v_sub_f32_e32 v40, v53, v33
	v_exp_f32_e32 v53, v32
	v_sub_f32_e32 v32, v129, v33
	v_sub_f32_e32 v43, v54, v33
	v_exp_f32_e32 v54, v32
	v_sub_f32_e32 v32, v130, v33
	v_sub_f32_e32 v42, v55, v33
	v_exp_f32_e32 v55, v32
	v_sub_f32_e32 v32, v131, v33
	v_sub_f32_e32 v45, v56, v33
	v_exp_f32_e32 v56, v32
	v_sub_f32_e32 v32, v132, v33
	v_sub_f32_e32 v44, v57, v33
	v_exp_f32_e32 v57, v32
	v_sub_f32_e32 v32, v133, v33
	v_sub_f32_e32 v47, v58, v33
	v_exp_f32_e32 v58, v32
	v_sub_f32_e32 v32, v134, v33
	v_sub_f32_e32 v46, v59, v33
	v_exp_f32_e32 v59, v32
	v_sub_f32_e32 v32, v135, v33
	v_sub_f32_e32 v36, v49, v33
	v_sub_f32_e32 v49, v60, v33
	v_exp_f32_e32 v60, v32
	v_sub_f32_e32 v32, v136, v33
	v_sub_f32_e32 v37, v48, v33
	v_sub_f32_e32 v48, v61, v33
	v_exp_f32_e32 v61, v32
	v_sub_f32_e32 v32, v137, v33
	v_sub_f32_e32 v38, v51, v33
	v_sub_f32_e32 v51, v62, v33
	v_exp_f32_e32 v62, v32
	v_sub_f32_e32 v32, v138, v33
	v_sub_f32_e32 v39, v50, v33
	v_sub_f32_e32 v50, v63, v33
	v_exp_f32_e32 v63, v32
	v_sub_f32_e32 v32, v139, v33
	v_sub_f32_e32 v35, v106, v33
	v_exp_f32_e32 v106, v32
	v_sub_f32_e32 v32, v140, v33
	v_add3_u32 v140, s0, v120, v121
	v_add_u32_e32 v144, 0x3000, v140
	v_add_u32_e32 v145, 0x4000, v140
	v_sub_f32_e32 v41, v52, v33
	v_sub_f32_e32 v52, v142, v33
	ds_read2_b64 v[132:135], v144 offset0:128 offset1:130
	ds_read2_b64 v[136:139], v144 offset0:132 offset1:134
	ds_read2_b64 v[140:143], v145 offset0:160 offset1:162
	v_sub_f32_e32 v128, v128, v33
	v_sub_f32_e32 v34, v107, v33
	v_exp_f32_e32 v34, v34
	v_exp_f32_e32 v35, v35
	v_exp_f32_e32 v36, v36
	v_exp_f32_e32 v37, v37
	v_exp_f32_e32 v38, v38
	v_exp_f32_e32 v39, v39
	v_exp_f32_e32 v40, v40
	v_exp_f32_e32 v41, v41
	v_exp_f32_e32 v107, v32
	v_exp_f32_e32 v32, v128
	v_cvt_pk_bf16_f32 v128, v34, v35
	v_cvt_pk_bf16_f32 v129, v36, v37
	v_cvt_pk_bf16_f32 v130, v38, v39
	v_pk_mul_f32 v[30:31], v[30:31], v[32:33] op_sel_hi:[1,0]
	v_pk_mul_f32 v[28:29], v[28:29], v[32:33] op_sel_hi:[1,0]
	v_pk_mul_f32 v[26:27], v[26:27], v[32:33] op_sel_hi:[1,0]
	v_pk_mul_f32 v[24:25], v[24:25], v[32:33] op_sel_hi:[1,0]
	v_pk_mul_f32 v[22:23], v[22:23], v[32:33] op_sel_hi:[1,0]
	v_pk_mul_f32 v[20:21], v[20:21], v[32:33] op_sel_hi:[1,0]
	v_pk_mul_f32 v[18:19], v[18:19], v[32:33] op_sel_hi:[1,0]
	v_pk_mul_f32 v[16:17], v[16:17], v[32:33] op_sel_hi:[1,0]
	v_cvt_pk_bf16_f32 v131, v40, v41
	v_pk_mul_f32 v[14:15], v[14:15], v[32:33] op_sel_hi:[1,0]
	v_pk_mul_f32 v[12:13], v[12:13], v[32:33] op_sel_hi:[1,0]
	v_pk_mul_f32 v[10:11], v[10:11], v[32:33] op_sel_hi:[1,0]
	v_pk_mul_f32 v[8:9], v[8:9], v[32:33] op_sel_hi:[1,0]
	v_pk_mul_f32 v[6:7], v[6:7], v[32:33] op_sel_hi:[1,0]
	v_pk_mul_f32 v[4:5], v[4:5], v[32:33] op_sel_hi:[1,0]
	v_pk_mul_f32 v[2:3], v[2:3], v[32:33] op_sel_hi:[1,0]
	v_pk_mul_f32 v[0:1], v[0:1], v[32:33] op_sel_hi:[1,0]
	s_waitcnt lgkmcnt(2)
	v_mfma_f32_32x32x16_bf16 v[16:31], v[132:135], v[128:131], v[16:31]
	ds_read2_b64 v[132:135], v145 offset0:164 offset1:166
	v_exp_f32_e32 v42, v42
	v_exp_f32_e32 v43, v43
	v_exp_f32_e32 v44, v44
	v_exp_f32_e32 v45, v45
	v_exp_f32_e32 v46, v46
	v_exp_f32_e32 v47, v47
	s_waitcnt lgkmcnt(1)
	v_mfma_f32_32x32x16_bf16 v[0:15], v[140:143], v[128:131], v[0:15]
	v_exp_f32_e32 v48, v48
	v_exp_f32_e32 v49, v49
	v_cvt_pk_bf16_f32 v128, v42, v43
	v_cvt_pk_bf16_f32 v129, v44, v45
	v_cvt_pk_bf16_f32 v130, v46, v47
	v_cvt_pk_bf16_f32 v131, v48, v49
	v_exp_f32_e32 v50, v50
	v_exp_f32_e32 v51, v51
	v_mfma_f32_32x32x16_bf16 v[16:31], v[136:139], v[128:131], v[16:31]
	v_exp_f32_e32 v52, v52
	s_waitcnt lgkmcnt(0)
	v_mfma_f32_32x32x16_bf16 v[0:15], v[132:135], v[128:131], v[0:15]
	ds_read2_b64 v[132:135], v144 offset0:136 offset1:138
	ds_read2_b64 v[136:139], v145 offset0:168 offset1:170
	v_cvt_pk_bf16_f32 v128, v50, v51
	v_cvt_pk_bf16_f32 v129, v52, v53
	v_cvt_pk_bf16_f32 v130, v54, v55
	v_cvt_pk_bf16_f32 v131, v56, v57
	s_nop 0
	s_nop 0
	s_waitcnt lgkmcnt(1)
	v_mfma_f32_32x32x16_bf16 v[16:31], v[132:135], v[128:131], v[16:31]
	s_waitcnt lgkmcnt(0)
	v_mfma_f32_32x32x16_bf16 v[0:15], v[136:139], v[128:131], v[0:15]
	ds_read2_b64 v[132:135], v144 offset0:140 offset1:142
	ds_read2_b64 v[136:139], v145 offset0:172 offset1:174
	v_cvt_pk_bf16_f32 v128, v58, v59
	v_cvt_pk_bf16_f32 v129, v60, v61
	v_cvt_pk_bf16_f32 v130, v62, v63
	v_cvt_pk_bf16_f32 v131, v106, v107
	s_nop 0
	s_nop 0
	s_waitcnt lgkmcnt(1)
	v_mfma_f32_32x32x16_bf16 v[16:31], v[132:135], v[128:131], v[16:31]
	s_waitcnt lgkmcnt(0)
	v_mfma_f32_32x32x16_bf16 v[0:15], v[136:139], v[128:131], v[0:15]
	s_cbranch_vccnz .LBB0_492
	s_xor_b32 s8, s8, 1
	s_mul_i32 s0, s8, 0x9000
	v_add3_u32 v129, s0, v114, v115
	v_lshlrev_b32_e32 v128, 2, v113
	s_waitcnt vmcnt(0)
	ds_write_b128 v129, v[80:83]
	v_add3_u32 v129, s0, v116, v117
	ds_write_b128 v129, v[84:87]
	v_add3_u32 v128, s0, v128, v112
	s_mov_b32 s1, 0x5040100
	s_mov_b32 s0, 0x7060302
	v_perm_b32 v129, v92, v88, s1
	v_perm_b32 v130, v92, v88, s0
	v_add_u32_e32 v128, 0x3400, v128
	ds_write2_b32 v128, v129, v130 offset1:34
	v_perm_b32 v129, v93, v89, s1
	v_perm_b32 v130, v93, v89, s0
	ds_write2_b32 v128, v129, v130 offset0:68 offset1:102
	v_perm_b32 v129, v94, v90, s1
	v_perm_b32 v130, v94, v90, s0
	ds_write2_b32 v128, v129, v130 offset0:136 offset1:170
	v_subrev_co_u32_e32 v126, vcc, 1, v126
	v_perm_b32 v129, v95, v91, s1
	v_perm_b32 v130, v95, v91, s0
	s_and_b64 vcc, exec, vcc
	ds_write2_b32 v128, v129, v130 offset0:204 offset1:238
	s_cbranch_vccnz .LBB0_491
	v_add_u32_e32 v90, 1, v123
	v_mad_i64_i32 v[80:81], s[0:1], v125, s17, v[102:103]
	v_mad_i64_i32 v[84:85], s[0:1], v124, s17, v[104:105]
	v_mad_u64_u32 v[88:89], s[0:1], v123, s17, v[100:101]
	v_mad_u64_u32 v[92:93], s[0:1], v90, s17, v[100:101]
	global_load_dwordx4 v[80:83], v[80:81], off offset:512
	s_nop 0
	global_load_dwordx4 v[84:87], v[84:85], off offset:512
	s_nop 0
	global_load_dwordx4 v[88:91], v[88:89], off offset:1024
	s_nop 0
	global_load_dwordx4 v[92:95], v[92:93], off offset:1024
